# neighbourhood attention unit start: query fragments and first K/V tile requested before the wait on the bias-row loads
# baseline (speedup 1.0000x reference)
.LBB0_608:
	v_add_u32_e32 v2, 64, v2
	s_movk_i32 s12, 0x73f
	v_cmp_lt_u32_e32 vcc, s12, v2
	ds_write_b32 v0, v1
	s_or_b64 s[10:11], vcc, s[10:11]
	v_add_u32_e32 v0, 0x100, v0
	s_andn2_b64 exec, exec, s[10:11]
	s_cbranch_execnz .LBB0_608
	s_or_b64 exec, exec, s[10:11]
	global_load_dword v0, v[152:153], off
	global_load_dword v3, v[152:153], off offset:256
	global_load_dword v4, v[152:153], off offset:512
	global_load_dword v5, v[152:153], off offset:768
	global_load_dword v6, v[152:153], off offset:1024
	global_load_dword v7, v[152:153], off offset:1280
	global_load_dword v8, v[152:153], off offset:1536
	s_mov_b64 s[24:25], exec
	s_andn2_b64 exec, exec, s[6:7]
	global_load_dword v9, v[152:153], off offset:1792
	s_mov_b64 exec, s[24:25]
	s_ashr_i32 s14, s22, 5
	s_bfe_u32 s13, s22, 0x40001
	s_lshl_b32 s12, s14, 10
	s_lshl_b32 s10, s13, 6
	s_lshl_b32 s11, s22, 5
	s_and_b32 s23, s11, 32
	s_or_b32 s10, s12, s10
	s_or_b32 s10, s10, s23
	s_addk_i32 s10, 0x2000
	s_ashr_i32 s11, s10, 31
	v_lshl_add_u64 v[10:11], v[134:135], 0, s[10:11]
	s_lshl_b32 s11, s14, 4
	s_add_i32 s14, s18, s11
	s_ashr_i32 s15, s14, 31
	v_lshlrev_b64 v[10:11], 7, v[10:11]
	s_lshl_b64 s[14:15], s[14:15], 15
	v_lshl_add_u64 v[10:11], v[136:137], 0, v[10:11]
	v_lshl_add_u64 v[166:167], v[148:149], 0, s[14:15]
	v_lshl_add_u64 v[168:169], v[150:151], 0, s[14:15]
	global_load_dwordx4 v[64:67], v[10:11], off
	global_load_dwordx4 v[68:71], v[10:11], off offset:32
	global_load_dwordx4 v[72:75], v[10:11], off offset:64
	global_load_dwordx4 v[76:79], v[10:11], off offset:96
	global_load_dwordx4 v[104:107], v[166:167], off
	global_load_dwordx4 v[100:103], v[166:167], off offset:1024
	global_load_dwordx4 v[108:111], v[166:167], off offset:2048
	global_load_dwordx4 v[112:115], v[166:167], off offset:3072
	global_load_dwordx4 v[92:95], v[168:169], off
	global_load_dwordx4 v[80:83], v[168:169], off offset:1024
	global_load_dwordx4 v[84:87], v[168:169], off offset:2048
	global_load_dwordx4 v[88:91], v[168:169], off offset:3072
	s_waitcnt vmcnt(12)
	v_mul_f32_e32 v2, 0x3fb8aa3b, v0
	v_mul_f32_e32 v3, 0x3fb8aa3b, v3
	v_mul_f32_e32 v4, 0x3fb8aa3b, v4
	v_mul_f32_e32 v5, 0x3fb8aa3b, v5
	v_mul_f32_e32 v6, 0x3fb8aa3b, v6
	v_mul_f32_e32 v7, 0x3fb8aa3b, v7
	v_mul_f32_e32 v0, 0x3fb8aa3b, v8
	v_mul_f32_e32 v9, 0x3fb8aa3b, v9
	ds_write_b32 v176, v2 offset:192
	ds_write_b32 v177, v3 offset:192
	ds_write_b32 v178, v4 offset:192
	ds_write_b32 v179, v5 offset:192
	ds_write_b32 v180, v6 offset:192
	ds_write_b32 v181, v7 offset:192
	ds_write_b32 v182, v0 offset:192
	s_mov_b64 s[24:25], exec
	s_andn2_b64 exec, exec, s[6:7]
	ds_write_b32 v186, v9 offset:192
	s_mov_b64 exec, s[24:25]
	v_mov_b32_e32 v14, v1
	v_mov_b32_e32 v15, v1
	v_mov_b32_e32 v0, v1
	v_mov_b32_e32 v2, v1
	v_mov_b32_e32 v3, v1
	v_mov_b32_e32 v4, v1
	v_mov_b32_e32 v5, v1
	v_mov_b32_e32 v6, v1
	v_mov_b32_e32 v7, v1
	v_mov_b32_e32 v8, v1
	v_mov_b32_e32 v9, v1
	v_mov_b32_e32 v10, v1
	v_mov_b32_e32 v11, v1
	v_mov_b32_e32 v12, v1
	v_mov_b32_e32 v13, v1
	v_mov_b64_e32 v[30:31], v[14:15]
	v_mov_b64_e32 v[46:47], v[14:15]
	s_lshr_b32 s11, s22, 1
	v_lshl_add_u64 v[170:171], v[154:155], 0, s[14:15]
	v_lshl_add_u64 v[172:173], v[156:157], 0, s[14:15]
	s_mov_b32 s24, 0
	v_mov_b32_e32 v224, 0
	v_mov_b32_e32 v192, 0xf149f2ca
	s_movk_i32 s25, 0x1000
	v_mov_b64_e32 v[28:29], v[12:13]
	v_mov_b64_e32 v[26:27], v[10:11]
	v_mov_b64_e32 v[24:25], v[8:9]
	v_mov_b64_e32 v[22:23], v[6:7]
	v_mov_b64_e32 v[20:21], v[4:5]
	v_mov_b64_e32 v[18:19], v[2:3]
	v_mov_b64_e32 v[16:17], v[0:1]
	v_mov_b64_e32 v[44:45], v[12:13]
	v_mov_b64_e32 v[42:43], v[10:11]
	v_mov_b64_e32 v[40:41], v[8:9]
	v_mov_b64_e32 v[38:39], v[6:7]
	v_mov_b64_e32 v[36:37], v[4:5]
	v_mov_b64_e32 v[34:35], v[2:3]
	v_mov_b64_e32 v[32:33], v[0:1]
	s_branch .LBB0_615
